# P1: MOD reduction loads issued up front into spare VGPRs, adds+stores deferred to the end of the phase (hides two load round trips in front of the norm)
# baseline (speedup 1.0000x reference)
.LBB0_82:
	s_or_b64 exec, exec, s[0:1]
	v_mov_b32_e32 v2, v250
	s_mov_b64 s[0:1], 0x36000
	v_ashrrev_i32_e32 v3, 31, v2
	v_lshl_add_u64 v[0:1], s[88:89], 0, v[2:3]
	v_cmp_gt_u64_e32 vcc, s[0:1], v[0:1]
	s_and_saveexec_b64 s[4:5], vcc
	v_readlane_b32 s12, v254, 2
	v_readlane_b32 s18, v254, 8
	v_readlane_b32 s19, v254, 9
	v_readlane_b32 s13, v254, 3
	v_readlane_b32 s14, v254, 4
	v_readlane_b32 s15, v254, 5
	v_readlane_b32 s16, v254, 6
	v_readlane_b32 s17, v254, 7
	v_readlane_b32 s20, v254, 10
	v_readlane_b32 s21, v254, 11
	v_readlane_b32 s22, v254, 12
	v_readlane_b32 s23, v254, 13
	v_readlane_b32 s24, v254, 14
	v_readlane_b32 s25, v254, 15
	v_readlane_b32 s26, v254, 16
	v_readlane_b32 s27, v254, 17
	s_cbranch_execz .LBB0_85
	s_lshl_b64 s[0:1], s[96:97], 11
	s_add_u32 s0, s50, s0
	s_addc_u32 s1, s51, s1
	v_lshl_add_u64 v[2:3], v[2:3], 2, s[0:1]
	s_mov_b64 s[0:1], 0x4780000
	v_lshl_add_u64 v[2:3], v[2:3], 0, s[0:1]
	s_lshl_b64 s[6:7], s[92:93], 11
	s_mov_b64 s[8:9], 0
	s_mov_b64 s[12:13], 0x1b000
	s_mov_b32 s2, 0xaaaaaaab
	v_mov_b32_e32 v6, 0x1800
	v_mov_b32_e32 v5, 0
	s_movk_i32 s3, 0x6000
	v_mov_b32_e32 v7, 0x48
	v_mov_b32_e32 v8, 0x5a
	v_mov_b32_e32 v9, 0x6c
	v_mov_b32_e32 v10, 0x7e
	v_mov_b32_e32 v11, 0x90
	v_mov_b32_e32 v12, 0xa2
	v_mov_b32_e32 v13, 0xb4
	v_mov_b32_e32 v14, 0xc6
	v_mov_b32_e32 v15, 0xd8
	v_mov_b32_e32 v16, 0xea
	v_bfrev_b32_e32 v17, 0.5
	v_mov_b32_e32 v18, 0x10e
	s_mov_b64 s[16:17], 0x35fff
	s_cmpk_eq_u32 s92, 0x100
	s_cbranch_scc0 .LBB0_84
	v_add_u32_e32 v4, 0xfffe5000, v0
	v_cmp_gt_u64_e32 vcc, s[12:13], v[0:1]
	s_mov_b64 s[0:1], 0x1afff
	v_cmp_lt_u64_e64 s[0:1], s[0:1], v[0:1]
	v_cndmask_b32_e32 v4, v4, v0, vcc
	v_mul_hi_u32 v29, v4, s2
	v_lshrrev_b32_e32 v29, 12, v29
	v_cndmask_b32_e64 v20, 0, 18, s[0:1]
	v_mul_u32_u24_e32 v30, 0x1800, v29
	v_mov_b32_e32 v21, v5
	v_cndmask_b32_e64 v19, 0, v6, s[0:1]
	v_cndmask_b32_e64 v22, 36, 54, s[0:1]
	v_cndmask_b32_e64 v23, v7, v8, s[0:1]
	v_cndmask_b32_e64 v24, v9, v10, s[0:1]
	v_cndmask_b32_e64 v25, v11, v12, s[0:1]
	v_cndmask_b32_e64 v26, v13, v14, s[0:1]
	v_cndmask_b32_e64 v27, v15, v16, s[0:1]
	v_cndmask_b32_e64 v28, v17, v18, s[0:1]
	v_add_u32_e32 v31, v20, v29
	v_sub_u32_e32 v20, v4, v30
	v_add_u32_e32 v32, v22, v29
	v_add_u32_e32 v33, v23, v29
	v_add_u32_e32 v34, v24, v29
	v_add_u32_e32 v35, v25, v29
	v_add_u32_e32 v36, v26, v29
	v_add_u32_e32 v37, v27, v29
	v_add_u32_e32 v38, v28, v29
	v_add_u32_e32 v4, v20, v19
	v_lshl_add_u64 v[20:21], v[20:21], 2, s[10:11]
	v_lshl_add_u64 v[22:23], v[4:5], 2, s[18:19]
	v_mad_u64_u32 v[24:25], s[0:1], v31, s3, v[20:21]
	v_mad_u64_u32 v[26:27], s[0:1], v32, s3, v[20:21]
	v_mad_u64_u32 v[28:29], s[0:1], v33, s3, v[20:21]
	v_mad_u64_u32 v[30:31], s[0:1], v34, s3, v[20:21]
	v_mad_u64_u32 v[32:33], s[0:1], v35, s3, v[20:21]
	v_mad_u64_u32 v[34:35], s[0:1], v36, s3, v[20:21]
	v_mad_u64_u32 v[36:37], s[0:1], v37, s3, v[20:21]
	v_mad_u64_u32 v[20:21], s[0:1], v38, s3, v[20:21]
	global_load_dword v144, v[22:23], off
	global_load_dword v145, v[24:25], off
	s_nop 0
	global_load_dword v146, v[26:27], off
	global_load_dword v147, v[28:29], off
	global_load_dword v148, v[30:31], off
	global_load_dword v149, v[32:33], off
	s_nop 0
	global_load_dword v150, v[34:35], off
	global_load_dword v151, v[36:37], off
	s_nop 0
	global_load_dword v152, v[20:21], off
	v_mov_b64_e32 v[162:163], v[2:3]
	v_lshl_add_u64 v[0:1], v[0:1], 0, s[34:35]
	v_lshl_add_u64 v[2:3], v[2:3], 0, s[6:7]
	v_cmp_lt_u64_e32 vcc, s[16:17], v[0:1]
	s_andn2_b64 exec, exec, vcc
	s_cbranch_execz .Lmod_e_done
	v_add_u32_e32 v4, 0xfffe5000, v0
	v_cmp_gt_u64_e32 vcc, s[12:13], v[0:1]
	s_mov_b64 s[0:1], 0x1afff
	v_cmp_lt_u64_e64 s[0:1], s[0:1], v[0:1]
	v_cndmask_b32_e32 v4, v4, v0, vcc
	v_mul_hi_u32 v29, v4, s2
	v_lshrrev_b32_e32 v29, 12, v29
	v_cndmask_b32_e64 v20, 0, 18, s[0:1]
	v_mul_u32_u24_e32 v30, 0x1800, v29
	v_mov_b32_e32 v21, v5
	v_cndmask_b32_e64 v19, 0, v6, s[0:1]
	v_cndmask_b32_e64 v22, 36, 54, s[0:1]
	v_cndmask_b32_e64 v23, v7, v8, s[0:1]
	v_cndmask_b32_e64 v24, v9, v10, s[0:1]
	v_cndmask_b32_e64 v25, v11, v12, s[0:1]
	v_cndmask_b32_e64 v26, v13, v14, s[0:1]
	v_cndmask_b32_e64 v27, v15, v16, s[0:1]
	v_cndmask_b32_e64 v28, v17, v18, s[0:1]
	v_add_u32_e32 v31, v20, v29
	v_sub_u32_e32 v20, v4, v30
	v_add_u32_e32 v32, v22, v29
	v_add_u32_e32 v33, v23, v29
	v_add_u32_e32 v34, v24, v29
	v_add_u32_e32 v35, v25, v29
	v_add_u32_e32 v36, v26, v29
	v_add_u32_e32 v37, v27, v29
	v_add_u32_e32 v38, v28, v29
	v_add_u32_e32 v4, v20, v19
	v_lshl_add_u64 v[20:21], v[20:21], 2, s[10:11]
	v_lshl_add_u64 v[22:23], v[4:5], 2, s[18:19]
	v_mad_u64_u32 v[24:25], s[0:1], v31, s3, v[20:21]
	v_mad_u64_u32 v[26:27], s[0:1], v32, s3, v[20:21]
	v_mad_u64_u32 v[28:29], s[0:1], v33, s3, v[20:21]
	v_mad_u64_u32 v[30:31], s[0:1], v34, s3, v[20:21]
	v_mad_u64_u32 v[32:33], s[0:1], v35, s3, v[20:21]
	v_mad_u64_u32 v[34:35], s[0:1], v36, s3, v[20:21]
	v_mad_u64_u32 v[36:37], s[0:1], v37, s3, v[20:21]
	v_mad_u64_u32 v[20:21], s[0:1], v38, s3, v[20:21]
	global_load_dword v153, v[22:23], off
	global_load_dword v154, v[24:25], off
	s_nop 0
	global_load_dword v155, v[26:27], off
	global_load_dword v156, v[28:29], off
	global_load_dword v157, v[30:31], off
	global_load_dword v158, v[32:33], off
	s_nop 0
	global_load_dword v159, v[34:35], off
	global_load_dword v160, v[36:37], off
	s_nop 0
	global_load_dword v161, v[20:21], off
	v_mov_b64_e32 v[164:165], v[2:3]
.Lmod_e_done:
	s_branch .LBB0_85
.LBB0_84:
	v_add_u32_e32 v4, 0xfffe5000, v0
	v_cmp_gt_u64_e32 vcc, s[12:13], v[0:1]
	s_mov_b64 s[0:1], 0x1afff
	v_cmp_lt_u64_e64 s[0:1], s[0:1], v[0:1]
	v_cndmask_b32_e32 v4, v4, v0, vcc
	v_mul_hi_u32 v29, v4, s2
	v_lshrrev_b32_e32 v29, 12, v29
	v_cndmask_b32_e64 v20, 0, 18, s[0:1]
	v_mul_u32_u24_e32 v30, 0x1800, v29
	v_mov_b32_e32 v21, v5
	v_cndmask_b32_e64 v19, 0, v6, s[0:1]
	v_cndmask_b32_e64 v22, 36, 54, s[0:1]
	v_cndmask_b32_e64 v23, v7, v8, s[0:1]
	v_cndmask_b32_e64 v24, v9, v10, s[0:1]
	v_cndmask_b32_e64 v25, v11, v12, s[0:1]
	v_cndmask_b32_e64 v26, v13, v14, s[0:1]
	v_cndmask_b32_e64 v27, v15, v16, s[0:1]
	v_cndmask_b32_e64 v28, v17, v18, s[0:1]
	v_add_u32_e32 v31, v20, v29
	v_sub_u32_e32 v20, v4, v30
	v_add_u32_e32 v32, v22, v29
	v_add_u32_e32 v33, v23, v29
	v_add_u32_e32 v34, v24, v29
	v_add_u32_e32 v35, v25, v29
	v_add_u32_e32 v36, v26, v29
	v_add_u32_e32 v37, v27, v29
	v_add_u32_e32 v38, v28, v29
	v_add_u32_e32 v4, v20, v19
	v_lshl_add_u64 v[20:21], v[20:21], 2, s[10:11]
	v_lshl_add_u64 v[22:23], v[4:5], 2, s[18:19]
	v_mad_u64_u32 v[24:25], s[0:1], v31, s3, v[20:21]
	v_mad_u64_u32 v[26:27], s[0:1], v32, s3, v[20:21]
	v_mad_u64_u32 v[28:29], s[0:1], v33, s3, v[20:21]
	v_mad_u64_u32 v[30:31], s[0:1], v34, s3, v[20:21]
	v_mad_u64_u32 v[32:33], s[0:1], v35, s3, v[20:21]
	v_mad_u64_u32 v[34:35], s[0:1], v36, s3, v[20:21]
	v_mad_u64_u32 v[36:37], s[0:1], v37, s3, v[20:21]
	v_mad_u64_u32 v[20:21], s[0:1], v38, s3, v[20:21]
	global_load_dword v4, v[22:23], off
	global_load_dword v19, v[24:25], off
	s_nop 0
	global_load_dword v22, v[26:27], off
	global_load_dword v23, v[28:29], off
	global_load_dword v24, v[30:31], off
	global_load_dword v25, v[32:33], off
	s_nop 0
	global_load_dword v26, v[34:35], off
	global_load_dword v27, v[36:37], off
	s_nop 0
	global_load_dword v20, v[20:21], off
	v_lshl_add_u64 v[0:1], v[0:1], 0, s[34:35]
	v_cmp_lt_u64_e32 vcc, s[16:17], v[0:1]
	s_or_b64 s[8:9], vcc, s[8:9]
	s_waitcnt vmcnt(7)
	v_add_f32_e32 v4, v4, v19
	s_waitcnt vmcnt(6)
	v_add_f32_e32 v4, v4, v22
	s_waitcnt vmcnt(5)
	v_add_f32_e32 v4, v4, v23
	s_waitcnt vmcnt(4)
	v_add_f32_e32 v4, v4, v24
	s_waitcnt vmcnt(3)
	v_add_f32_e32 v4, v4, v25
	s_waitcnt vmcnt(2)
	v_add_f32_e32 v4, v4, v26
	s_waitcnt vmcnt(1)
	v_add_f32_e32 v4, v4, v27
	s_waitcnt vmcnt(0)
	v_add_f32_e32 v4, v4, v20
	global_store_dword v[2:3], v4, off
	v_lshl_add_u64 v[2:3], v[2:3], 0, s[6:7]
	s_andn2_b64 exec, exec, s[8:9]
	s_cbranch_execnz .LBB0_84

.LBB0_101:
	s_cmpk_eq_u32 s92, 0x100
	s_cbranch_scc0 .Lmod_l_done
	s_waitcnt vmcnt(0)
	v_add_f32_e32 v144, v144, v145
	v_add_f32_e32 v144, v144, v146
	v_add_f32_e32 v144, v144, v147
	v_add_f32_e32 v144, v144, v148
	v_add_f32_e32 v144, v144, v149
	v_add_f32_e32 v144, v144, v150
	v_add_f32_e32 v144, v144, v151
	v_add_f32_e32 v144, v144, v152
	global_store_dword v[162:163], v144, off
	s_lshl_b32 s98, s96, 9
	v_add_u32_e32 v166, s98, v250
	v_cmp_gt_u32_e32 vcc, 0x16000, v166
	s_mov_b64 s[98:99], exec
	s_and_b64 exec, exec, vcc
	s_cbranch_execz .Lmod_l_skipb
	v_add_f32_e32 v153, v153, v154
	v_add_f32_e32 v153, v153, v155
	v_add_f32_e32 v153, v153, v156
	v_add_f32_e32 v153, v153, v157
	v_add_f32_e32 v153, v153, v158
	v_add_f32_e32 v153, v153, v159
	v_add_f32_e32 v153, v153, v160
	v_add_f32_e32 v153, v153, v161
	global_store_dword v[164:165], v153, off
.Lmod_l_skipb:
	s_mov_b64 exec, s[98:99]
